# baseline (speedup 1.0000x reference)
; DI int crow(int reg, int h) { return (reg & 3) + 8 * (reg >> 2) + 4 * h; }
; template <int MASK>
; __global__ void __launch_bounds__(256, 2) fwd_megakernel_t(Params p) {
;     ...
; #pragma unroll
;         for (int i = 0; i < 2; i++) {
;           float rv[16];
; #pragma unroll
;           for (int r = 0; r < 16; r++) rv[r] = s_rinv[wm * 64 + i * 32 + crow(r, hh)];
; #pragma unroll
;           for (int j = 0; j < 2; j++) {
;             const int n = n0 + wn * 64 + j * 32 + cc;
;             if (isq) {
; #pragma unroll
;               for (int r = 0; r < 16; r++) qraw[(size_t)(m0 + wm * 64 + i * 32 + crow(r, hh)) * 1152 + n] = f2bf(acc[i][j][r] * rv[r]);
;             } else {
;               const int hd = n0 >> 8;
;               if (((n0 >> 7) & 1) == 0) {
; #pragma unroll
;                 for (int r = 0; r < 16; r++)
;                   knope[(size_t)(m0 + wm * 64 + i * 32 + crow(r, hh)) * 768 + hd * 128 + (n & 127)] = f2bf(acc[i][j][r] * rv[r]);
.LBB0_531:
	s_andn2_b64 vcc, exec, s[8:9]
	v_or_b32_e32 v99, 1, v84
	v_or_b32_e32 v98, 2, v84
	v_or_b32_e32 v97, 3, v84
	v_or_b32_e32 v96, 8, v84
	v_or_b32_e32 v95, 9, v84
	v_or_b32_e32 v94, 10, v84
	v_or_b32_e32 v93, 11, v84
	v_or_b32_e32 v92, 16, v84
	v_or_b32_e32 v91, 17, v84
	v_or_b32_e32 v90, 18, v84
	v_or_b32_e32 v89, 19, v84
	v_or_b32_e32 v88, 24, v84
	v_or_b32_e32 v87, 25, v84
	v_or_b32_e32 v86, 26, v84
	v_or_b32_e32 v85, 27, v84
	v_or_b32_e32 v82, s30, v130
	s_cbranch_vccnz .LBB0_533
	v_ashrrev_i32_e32 v83, 31, v82
	v_lshl_add_u64 v[100:101], v[82:83], 1, s[92:93]
	v_cvt_pk_bf16_f32 v48, v48, s0
	v_mad_i64_i32 v[102:103], s[8:9], v84, s90, v[100:101]
	global_store_short v[102:103], v48, off
	v_mul_f32_e32 v48, v49, v77
	v_cvt_pk_bf16_f32 v81, v48, s0
	v_mad_i64_i32 v[48:49], s[8:9], v99, s90, v[100:101]
	global_store_short v[48:49], v81, off
	v_mul_f32_e32 v48, v50, v78
	v_cvt_pk_bf16_f32 v50, v48, s0
	v_mad_i64_i32 v[48:49], s[8:9], v98, s90, v[100:101]
	global_store_short v[48:49], v50, off
	v_mul_f32_e32 v48, v51, v79
	v_cvt_pk_bf16_f32 v50, v48, s0
	v_mad_i64_i32 v[48:49], s[8:9], v97, s90, v[100:101]
	global_store_short v[48:49], v50, off
	s_waitcnt lgkmcnt(2)
	v_mul_f32_e32 v48, v52, v72
	v_cvt_pk_bf16_f32 v50, v48, s0
	v_mad_i64_i32 v[48:49], s[8:9], v96, s90, v[100:101]
	global_store_short v[48:49], v50, off
	v_mul_f32_e32 v48, v53, v73
	v_cvt_pk_bf16_f32 v50, v48, s0
	v_mad_i64_i32 v[48:49], s[8:9], v95, s90, v[100:101]
	global_store_short v[48:49], v50, off
	v_mul_f32_e32 v48, v54, v74
	v_cvt_pk_bf16_f32 v50, v48, s0
	v_mad_i64_i32 v[48:49], s[8:9], v94, s90, v[100:101]
	global_store_short v[48:49], v50, off
	v_mul_f32_e32 v48, v55, v75
	v_cvt_pk_bf16_f32 v50, v48, s0
	v_mad_i64_i32 v[48:49], s[8:9], v93, s90, v[100:101]
	global_store_short v[48:49], v50, off
	s_waitcnt lgkmcnt(1)
	v_mul_f32_e32 v48, v56, v68
	v_cvt_pk_bf16_f32 v50, v48, s0
	v_mad_i64_i32 v[48:49], s[8:9], v92, s90, v[100:101]
	global_store_short v[48:49], v50, off
	v_mul_f32_e32 v48, v57, v69
	v_cvt_pk_bf16_f32 v50, v48, s0
	v_mad_i64_i32 v[48:49], s[8:9], v91, s90, v[100:101]
	global_store_short v[48:49], v50, off
	v_mul_f32_e32 v48, v58, v70
	v_cvt_pk_bf16_f32 v50, v48, s0
	v_mad_i64_i32 v[48:49], s[8:9], v90, s90, v[100:101]
	global_store_short v[48:49], v50, off
	v_mul_f32_e32 v48, v59, v71
	v_cvt_pk_bf16_f32 v50, v48, s0
	v_mad_i64_i32 v[48:49], s[8:9], v89, s90, v[100:101]
	global_store_short v[48:49], v50, off
	s_waitcnt lgkmcnt(0)
	v_mul_f32_e32 v48, v60, v64
	v_cvt_pk_bf16_f32 v50, v48, s0
	v_mad_i64_i32 v[48:49], s[8:9], v88, s90, v[100:101]
	global_store_short v[48:49], v50, off
	v_mul_f32_e32 v48, v61, v65
	v_cvt_pk_bf16_f32 v50, v48, s0
	v_mad_i64_i32 v[48:49], s[8:9], v87, s90, v[100:101]
	global_store_short v[48:49], v50, off
	v_mul_f32_e32 v48, v62, v66
	v_cvt_pk_bf16_f32 v50, v48, s0
	v_mad_i64_i32 v[48:49], s[8:9], v86, s90, v[100:101]
	global_store_short v[48:49], v50, off
	v_mul_f32_e32 v48, v63, v67
	v_cvt_pk_bf16_f32 v50, v48, s0
	v_mad_i64_i32 v[48:49], s[8:9], v85, s90, v[100:101]
	global_store_short v[48:49], v50, off

; DI void convT_all(KP pp, char* ws, float* lds, int tid) {
;     ...
;     __syncthreads();
;     {
;       float4 v[16];
;       const float* sp = src + (size_t)(k0 + kr) * Nsrc + sn;
; #pragma unroll
;       for (int ps = 0; ps < 16; ps++) v[ps] = zero ? make_float4(0.f, 0.f, 0.f, 0.f) : *(const float4*)(sp + (size_t)ps * 8 * Nsrc);
; #pragma unroll
;       for (int ps = 0; ps < 16; ps++) {
;         const float g = gain ? gain[k0 + kr + ps * 8] : 1.f;
;         float* lp = lds + (kr + ps * 8) * 129 + n4 * 4;
;         lp[0] = v[ps].x * g; lp[1] = v[ps].y * g; lp[2] = v[ps].z * g; lp[3] = v[ps].w * g;
;       }
.LBB0_641:
	s_or_b64 exec, exec, s[16:17]
	s_cmp_lg_u64 s[12:13], 0
	s_cselect_b64 s[14:15], -1, 0
	s_cmp_eq_u64 s[12:13], 0
	v_lshl_add_u64 v[66:67], v[66:67], 2, s[12:13]
	v_add_u32_e32 v78, 0x1020, v77
	v_add_u32_e32 v79, 0x1028, v77
	s_cbranch_scc1 .LBB0_652
	global_load_dword v100, v[66:67], off
	global_load_dword v101, v[66:67], off offset:32
	global_load_dword v102, v[66:67], off offset:64
	global_load_dword v103, v[66:67], off offset:96
	global_load_dword v104, v[66:67], off offset:128
	global_load_dword v105, v[66:67], off offset:160
	global_load_dword v106, v[66:67], off offset:192
	global_load_dword v107, v[66:67], off offset:224
	global_load_dword v108, v[66:67], off offset:256
	global_load_dword v109, v[66:67], off offset:288
	global_load_dword v110, v[66:67], off offset:320
	global_load_dword v111, v[66:67], off offset:352
	global_load_dword v112, v[66:67], off offset:384
	global_load_dword v113, v[66:67], off offset:416
	global_load_dword v114, v[66:67], off offset:448
	global_load_dword v115, v[66:67], off offset:480
	s_waitcnt vmcnt(0)
	s_nop 1
	v_mov_b32_e32 v68, v100
	s_nop 1
	v_mov_b32_e32 v72, v101
	s_waitcnt vmcnt(1)
	v_pk_mul_f32 v[70:71], v[52:53], v[68:69] op_sel_hi:[1,0]
	v_pk_mul_f32 v[68:69], v[54:55], v[68:69] op_sel_hi:[1,0]
	ds_write2_b32 v77, v70, v71 offset1:1
	ds_write2_b32 v77, v68, v69 offset0:2 offset1:3
	s_waitcnt vmcnt(0)
	v_pk_mul_f32 v[68:69], v[48:49], v[72:73] op_sel_hi:[1,0]
	ds_write2_b32 v78, v68, v69 offset1:1
	v_pk_mul_f32 v[68:69], v[50:51], v[72:73] op_sel_hi:[1,0]
	ds_write2_b32 v79, v68, v69 offset1:1
	s_nop 1
	v_mov_b32_e32 v68, v102
	s_nop 1
	v_mov_b32_e32 v72, v103
	s_waitcnt vmcnt(1)
	v_pk_mul_f32 v[70:71], v[56:57], v[68:69] op_sel_hi:[1,0]
	v_pk_mul_f32 v[68:69], v[58:59], v[68:69] op_sel_hi:[1,0]
	s_cbranch_execnz .LBB0_644

; DI void convT_all(KP pp, char* ws, float* lds, int tid) {
;     ...
;     __syncthreads();
;     {
;       float4 v[16];
;       const float* sp = src + (size_t)(k0 + kr) * Nsrc + sn;
; #pragma unroll
;       for (int ps = 0; ps < 16; ps++) v[ps] = zero ? make_float4(0.f, 0.f, 0.f, 0.f) : *(const float4*)(sp + (size_t)ps * 8 * Nsrc);
; #pragma unroll
;       for (int ps = 0; ps < 16; ps++) {
;         const float g = gain ? gain[k0 + kr + ps * 8] : 1.f;
;         float* lp = lds + (kr + ps * 8) * 129 + n4 * 4;
;         lp[0] = v[ps].x * g; lp[1] = v[ps].y * g; lp[2] = v[ps].z * g; lp[3] = v[ps].w * g;
;       }
.LBB0_644:
	v_add_u32_e32 v48, 0x2040, v77
	ds_write2_b32 v48, v70, v71 offset1:1
	v_add_u32_e32 v48, 0x2048, v77
	ds_write2_b32 v48, v68, v69 offset1:1
	s_waitcnt vmcnt(0)
	v_pk_mul_f32 v[48:49], v[60:61], v[72:73] op_sel_hi:[1,0]
	v_add_u32_e32 v50, 0x3060, v77
	ds_write2_b32 v50, v48, v49 offset1:1
	v_pk_mul_f32 v[48:49], v[62:63], v[72:73] op_sel_hi:[1,0]
	v_add_u32_e32 v50, 0x3068, v77
	ds_write2_b32 v50, v48, v49 offset1:1
	v_cndmask_b32_e64 v48, 0, 1, s[14:15]
	v_cmp_ne_u32_e64 s[6:7], 1, v48
	s_andn2_b64 vcc, exec, s[14:15]
	v_add_u32_e32 v53, 0x4080, v77
	v_add_u32_e32 v54, 0x4088, v77
	v_add_u32_e32 v55, 0x50a0, v77
	v_add_u32_e32 v56, 0x50a8, v77
	s_cbranch_vccnz .LBB0_653
	s_nop 1
	v_mov_b32_e32 v48, v104
	s_nop 1
	v_mov_b32_e32 v52, v105
	s_waitcnt vmcnt(1)
	v_pk_mul_f32 v[50:51], v[20:21], v[48:49] op_sel_hi:[1,0]
	v_pk_mul_f32 v[48:49], v[22:23], v[48:49] op_sel_hi:[1,0]
	ds_write2_b32 v53, v50, v51 offset1:1
	ds_write2_b32 v54, v48, v49 offset1:1
	s_waitcnt vmcnt(0)
	v_pk_mul_f32 v[48:49], v[36:37], v[52:53] op_sel_hi:[1,0]
	ds_write2_b32 v55, v48, v49 offset1:1
	v_pk_mul_f32 v[48:49], v[38:39], v[52:53] op_sel_hi:[1,0]
	ds_write2_b32 v56, v48, v49 offset1:1
	s_nop 1
	v_mov_b32_e32 v48, v106
	s_nop 1
	v_mov_b32_e32 v52, v107
	s_waitcnt vmcnt(1)
	v_pk_mul_f32 v[50:51], v[40:41], v[48:49] op_sel_hi:[1,0]
	v_pk_mul_f32 v[48:49], v[42:43], v[48:49] op_sel_hi:[1,0]
	s_cbranch_execnz .LBB0_647

; DI void convT_all(KP pp, char* ws, float* lds, int tid) {
;     ...
;     __syncthreads();
;     {
;       float4 v[16];
;       const float* sp = src + (size_t)(k0 + kr) * Nsrc + sn;
; #pragma unroll
;       for (int ps = 0; ps < 16; ps++) v[ps] = zero ? make_float4(0.f, 0.f, 0.f, 0.f) : *(const float4*)(sp + (size_t)ps * 8 * Nsrc);
; #pragma unroll
;       for (int ps = 0; ps < 16; ps++) {
;         const float g = gain ? gain[k0 + kr + ps * 8] : 1.f;
;         float* lp = lds + (kr + ps * 8) * 129 + n4 * 4;
;         lp[0] = v[ps].x * g; lp[1] = v[ps].y * g; lp[2] = v[ps].z * g; lp[3] = v[ps].w * g;
;       }
.LBB0_647:
	v_add_u32_e32 v20, 0x60c0, v77
	ds_write2_b32 v20, v50, v51 offset1:1
	v_add_u32_e32 v20, 0x60c8, v77
	ds_write2_b32 v20, v48, v49 offset1:1
	s_waitcnt vmcnt(0)
	v_pk_mul_f32 v[20:21], v[44:45], v[52:53] op_sel_hi:[1,0]
	v_add_u32_e32 v22, 0x70e0, v77
	ds_write2_b32 v22, v20, v21 offset1:1
	v_pk_mul_f32 v[20:21], v[46:47], v[52:53] op_sel_hi:[1,0]
	v_add_u32_e32 v22, 0x70e8, v77
	s_and_b64 vcc, exec, s[6:7]
	v_add_u32_e32 v37, 0x8100, v77
	v_add_u32_e32 v38, 0x8108, v77
	v_add_u32_e32 v39, 0x9120, v77
	v_add_u32_e32 v40, 0x9128, v77
	ds_write2_b32 v22, v20, v21 offset1:1
	s_cbranch_vccnz .LBB0_654
	s_nop 1
	v_mov_b32_e32 v20, v108
	s_nop 1
	v_mov_b32_e32 v36, v109
	s_waitcnt vmcnt(1)
	v_pk_mul_f32 v[22:23], v[4:5], v[20:21] op_sel_hi:[1,0]
	v_pk_mul_f32 v[20:21], v[6:7], v[20:21] op_sel_hi:[1,0]
	ds_write2_b32 v37, v22, v23 offset1:1
	ds_write2_b32 v38, v20, v21 offset1:1
	s_waitcnt vmcnt(0)
	v_pk_mul_f32 v[20:21], v[24:25], v[36:37] op_sel_hi:[1,0]
	ds_write2_b32 v39, v20, v21 offset1:1
	v_pk_mul_f32 v[20:21], v[26:27], v[36:37] op_sel_hi:[1,0]
	ds_write2_b32 v40, v20, v21 offset1:1
	s_nop 1
	v_mov_b32_e32 v20, v110
	s_nop 1
	v_mov_b32_e32 v36, v111
	s_waitcnt vmcnt(1)
	v_pk_mul_f32 v[22:23], v[28:29], v[20:21] op_sel_hi:[1,0]
	v_pk_mul_f32 v[20:21], v[30:31], v[20:21] op_sel_hi:[1,0]
	s_cbranch_execnz .LBB0_650

; DI void convT_all(KP pp, char* ws, float* lds, int tid) {
;     ...
;     __syncthreads();
;     {
;       float4 v[16];
;       const float* sp = src + (size_t)(k0 + kr) * Nsrc + sn;
; #pragma unroll
;       for (int ps = 0; ps < 16; ps++) v[ps] = zero ? make_float4(0.f, 0.f, 0.f, 0.f) : *(const float4*)(sp + (size_t)ps * 8 * Nsrc);
; #pragma unroll
;       for (int ps = 0; ps < 16; ps++) {
;         const float g = gain ? gain[k0 + kr + ps * 8] : 1.f;
;         float* lp = lds + (kr + ps * 8) * 129 + n4 * 4;
;         lp[0] = v[ps].x * g; lp[1] = v[ps].y * g; lp[2] = v[ps].z * g; lp[3] = v[ps].w * g;
;       }
.LBB0_650:
	v_add_u32_e32 v4, 0xa140, v77
	ds_write2_b32 v4, v22, v23 offset1:1
	v_add_u32_e32 v4, 0xa148, v77
	ds_write2_b32 v4, v20, v21 offset1:1
	s_waitcnt vmcnt(0)
	v_pk_mul_f32 v[4:5], v[32:33], v[36:37] op_sel_hi:[1,0]
	v_add_u32_e32 v6, 0xb160, v77
	ds_write2_b32 v6, v4, v5 offset1:1
	v_pk_mul_f32 v[4:5], v[34:35], v[36:37] op_sel_hi:[1,0]
	v_add_u32_e32 v6, 0xb168, v77
	s_and_b64 vcc, exec, s[6:7]
	v_add_u32_e32 v21, 0xc180, v77
	v_add_u32_e32 v22, 0xc188, v77
	v_add_u32_e32 v23, 0xd1a0, v77
	v_add_u32_e32 v24, 0xd1a8, v77
	ds_write2_b32 v6, v4, v5 offset1:1
	s_cbranch_vccnz .LBB0_655
	s_nop 1
	v_mov_b32_e32 v4, v112
	s_nop 1
	v_mov_b32_e32 v20, v113
	s_waitcnt vmcnt(1)
	v_pk_mul_f32 v[6:7], v[0:1], v[4:5] op_sel_hi:[1,0]
	v_pk_mul_f32 v[4:5], v[2:3], v[4:5] op_sel_hi:[1,0]
	ds_write2_b32 v21, v6, v7 offset1:1
	ds_write2_b32 v22, v4, v5 offset1:1
	s_waitcnt vmcnt(0)
	v_pk_mul_f32 v[4:5], v[8:9], v[20:21] op_sel_hi:[1,0]
	ds_write2_b32 v23, v4, v5 offset1:1
	v_pk_mul_f32 v[4:5], v[10:11], v[20:21] op_sel_hi:[1,0]
	ds_write2_b32 v24, v4, v5 offset1:1
	s_nop 1
	v_mov_b32_e32 v4, v114
	s_nop 1
	v_mov_b32_e32 v20, v115
	s_waitcnt vmcnt(1)
	v_pk_mul_f32 v[6:7], v[12:13], v[4:5] op_sel_hi:[1,0]
	v_pk_mul_f32 v[4:5], v[14:15], v[4:5] op_sel_hi:[1,0]
	s_cbranch_execnz .LBB0_580
	s_branch .LBB0_656

; DI int crow(int reg, int h) { return (reg & 3) + 8 * (reg >> 2) + 4 * h; }
; template <int MASK>
; __global__ void __launch_bounds__(256, 2) fwd_megakernel_t(Params p) {
;     ...
; #pragma unroll
;         for (int i = 0; i < 2; i++) {
;           float rv[16];
; #pragma unroll
;           for (int r = 0; r < 16; r++) rv[r] = rinvx[m0 + wm * 64 + i * 32 + crow(r, hh)];
; #pragma unroll
;           for (int j = 0; j < 2; j++) {
;             const int n = n0 + wn * 64 + j * 32 + cc;
;             if (n0 >= C_GATE) {
;               const int br = (n0 - C_GATE) >> 11, ntg = ((n0 - C_GATE) & 2047) >> 7;
;               u16* gdst = gbuf + ((size_t)((((br * 128 + mt) * 16 + ntg) * 4 + wave) * 64 + lane)) * 64 + (i * 2 + j) * 16;
;               unsigned gw[8];
; #pragma unroll
;               for (int r = 0; r < 16; r += 2)
;                 gw[r >> 1] = pack2(1.f / (1.f + __expf(-acc[i][j][r] * rv[r])), 1.f / (1.f + __expf(-acc[i][j][r + 1] * rv[r + 1])));
;               *(uint4*)(gdst) = make_uint4(gw[0], gw[1], gw[2], gw[3]);
;               *(uint4*)(gdst + 8) = make_uint4(gw[4], gw[5], gw[6], gw[7]);
;             } else if (!isv) {
;               if (n0 == C_KR && n >= C_KR + 64) continue;
; #pragma unroll
;               for (int r = 0; r < 16; r++) {
;                 const int m = m0 + wm * 64 + i * 32 + crow(r, hh);
;                 proj[(size_t)m * NPJ + n] = f2bf(acc[i][j][r] * rv[r]);
;               }
;             } else if (n0 < C_DQ) {
;               const int hd = (n0 - C_SBV) >> 7, d = n & 127;
;               u16* dst = sbvT + ((size_t)(b * 4 + hd) * 128 + d) * S_;
; #pragma unroll
;               for (int rg = 0; rg < 4; rg++) {
;                 const int s = (m0 - b * S_) + wm * 64 + i * 32 + 8 * rg + 4 * hh;
;                 uint2 w;
;                 w.x = pack2(acc[i][j][rg * 4 + 0] * rv[rg * 4 + 0], acc[i][j][rg * 4 + 1] * rv[rg * 4 + 1]);
;                 w.y = pack2(acc[i][j][rg * 4 + 2] * rv[rg * 4 + 2], acc[i][j][rg * 4 + 3] * rv[rg * 4 + 3]);
;                 *(uint2*)(dst + s) = w;
;               }
.Lp1_sbv:
	v_add_u32_e32 v64, s10, v137
	v_ashrrev_i32_e32 v65, 31, v64
	v_lshl_add_u64 v[66:67], v[64:65], 2, s[80:81]
	global_load_dwordx4 v[68:71], v[66:67], off
	global_load_dwordx4 v[72:75], v[66:67], off offset:32
	global_load_dwordx4 v[76:79], v[66:67], off offset:64
	global_load_dwordx4 v[80:83], v[66:67], off offset:96
	global_load_dwordx4 v[84:87], v[66:67], off offset:128
	global_load_dwordx4 v[88:91], v[66:67], off offset:160
	global_load_dwordx4 v[92:95], v[66:67], off offset:192
	global_load_dwordx4 v[96:99], v[66:67], off offset:224
	v_and_b32_e32 v100, 31, v152
	v_bfe_u32 v101, v152, 5, 1
	v_bfe_u32 v102, v152, 6, 1
	v_lshrrev_b32_e32 v103, 7, v152
	v_lshl_add_u32 v104, v102, 6, v100
	v_mul_u32_u24_e32 v104, 0x104, v104
	v_lshlrev_b32_e32 v105, 7, v103
	v_lshl_add_u32 v105, v101, 3, v105
	v_add_u32_e32 v104, v104, v105
	s_waitcnt vmcnt(0)
	v_mul_f32_e32 v48, v48, v68
	v_mul_f32_e32 v49, v49, v69
	v_cvt_pk_bf16_f32 v48, v48, v49
	ds_write_b32 v104, v48
	v_mul_f32_e32 v50, v50, v70
	v_mul_f32_e32 v51, v51, v71
	v_cvt_pk_bf16_f32 v50, v50, v51
	ds_write_b32 v104, v50 offset:4
	v_mul_f32_e32 v52, v52, v72
	v_mul_f32_e32 v53, v53, v73
	v_cvt_pk_bf16_f32 v52, v52, v53
	ds_write_b32 v104, v52 offset:16
	v_mul_f32_e32 v54, v54, v74
	v_mul_f32_e32 v55, v55, v75
	v_cvt_pk_bf16_f32 v54, v54, v55
	ds_write_b32 v104, v54 offset:20
	v_mul_f32_e32 v56, v56, v76
	v_mul_f32_e32 v57, v57, v77
	v_cvt_pk_bf16_f32 v56, v56, v57
	ds_write_b32 v104, v56 offset:32
	v_mul_f32_e32 v58, v58, v78
	v_mul_f32_e32 v59, v59, v79
	v_cvt_pk_bf16_f32 v58, v58, v59
	ds_write_b32 v104, v58 offset:36
	v_mul_f32_e32 v60, v60, v80
	v_mul_f32_e32 v61, v61, v81
	v_cvt_pk_bf16_f32 v60, v60, v61
	ds_write_b32 v104, v60 offset:48
	v_mul_f32_e32 v62, v62, v82
	v_mul_f32_e32 v63, v63, v83
	v_cvt_pk_bf16_f32 v62, v62, v63
	ds_write_b32 v104, v62 offset:52
	v_mul_f32_e32 v32, v32, v68
	v_mul_f32_e32 v33, v33, v69
	v_cvt_pk_bf16_f32 v32, v32, v33
	ds_write_b32 v104, v32 offset:8320
	v_mul_f32_e32 v34, v34, v70
	v_mul_f32_e32 v35, v35, v71
	v_cvt_pk_bf16_f32 v34, v34, v35
	ds_write_b32 v104, v34 offset:8324
	v_mul_f32_e32 v36, v36, v72
	v_mul_f32_e32 v37, v37, v73
	v_cvt_pk_bf16_f32 v36, v36, v37
	ds_write_b32 v104, v36 offset:8336
	v_mul_f32_e32 v38, v38, v74
	v_mul_f32_e32 v39, v39, v75
	v_cvt_pk_bf16_f32 v38, v38, v39
	ds_write_b32 v104, v38 offset:8340
	v_mul_f32_e32 v40, v40, v76
	v_mul_f32_e32 v41, v41, v77
	v_cvt_pk_bf16_f32 v40, v40, v41
	ds_write_b32 v104, v40 offset:8352
	v_mul_f32_e32 v42, v42, v78
	v_mul_f32_e32 v43, v43, v79
	v_cvt_pk_bf16_f32 v42, v42, v43
	ds_write_b32 v104, v42 offset:8356
	v_mul_f32_e32 v44, v44, v80
	v_mul_f32_e32 v45, v45, v81
	v_cvt_pk_bf16_f32 v44, v44, v45
	ds_write_b32 v104, v44 offset:8368
	v_mul_f32_e32 v46, v46, v82
	v_mul_f32_e32 v47, v47, v83
	v_cvt_pk_bf16_f32 v46, v46, v47
	ds_write_b32 v104, v46 offset:8372
	v_mul_f32_e32 v16, v16, v84
	v_mul_f32_e32 v17, v17, v85
	v_cvt_pk_bf16_f32 v16, v16, v17
	ds_write_b32 v104, v16 offset:64
	v_mul_f32_e32 v18, v18, v86
	v_mul_f32_e32 v19, v19, v87
	v_cvt_pk_bf16_f32 v18, v18, v19
	ds_write_b32 v104, v18 offset:68
	v_mul_f32_e32 v20, v20, v88
	v_mul_f32_e32 v21, v21, v89
	v_cvt_pk_bf16_f32 v20, v20, v21
	ds_write_b32 v104, v20 offset:80
	v_mul_f32_e32 v22, v22, v90
	v_mul_f32_e32 v23, v23, v91
	v_cvt_pk_bf16_f32 v22, v22, v23
	ds_write_b32 v104, v22 offset:84
	v_mul_f32_e32 v24, v24, v92
	v_mul_f32_e32 v25, v25, v93
	v_cvt_pk_bf16_f32 v24, v24, v25
	ds_write_b32 v104, v24 offset:96
	v_mul_f32_e32 v26, v26, v94
	v_mul_f32_e32 v27, v27, v95
	v_cvt_pk_bf16_f32 v26, v26, v27
	ds_write_b32 v104, v26 offset:100
	v_mul_f32_e32 v28, v28, v96
	v_mul_f32_e32 v29, v29, v97
	v_cvt_pk_bf16_f32 v28, v28, v29
	ds_write_b32 v104, v28 offset:112
	v_mul_f32_e32 v30, v30, v98
	v_mul_f32_e32 v31, v31, v99
	v_cvt_pk_bf16_f32 v30, v30, v31
	ds_write_b32 v104, v30 offset:116
	v_mul_f32_e32 v0, v0, v84
	v_mul_f32_e32 v1, v1, v85
	v_cvt_pk_bf16_f32 v0, v0, v1
	ds_write_b32 v104, v0 offset:8384
	v_mul_f32_e32 v2, v2, v86
	v_mul_f32_e32 v3, v3, v87
	v_cvt_pk_bf16_f32 v2, v2, v3
	ds_write_b32 v104, v2 offset:8388
	v_mul_f32_e32 v4, v4, v88
	v_mul_f32_e32 v5, v5, v89
	v_cvt_pk_bf16_f32 v4, v4, v5
	ds_write_b32 v104, v4 offset:8400
	v_mul_f32_e32 v6, v6, v90
	v_mul_f32_e32 v7, v7, v91
	v_cvt_pk_bf16_f32 v6, v6, v7
	ds_write_b32 v104, v6 offset:8404
	v_mul_f32_e32 v8, v8, v92
	v_mul_f32_e32 v9, v9, v93
	v_cvt_pk_bf16_f32 v8, v8, v9
	ds_write_b32 v104, v8 offset:8416
	v_mul_f32_e32 v10, v10, v94
	v_mul_f32_e32 v11, v11, v95
	v_cvt_pk_bf16_f32 v10, v10, v11
	ds_write_b32 v104, v10 offset:8420
	v_mul_f32_e32 v12, v12, v96
	v_mul_f32_e32 v13, v13, v97
	v_cvt_pk_bf16_f32 v12, v12, v13
	ds_write_b32 v104, v12 offset:8432
	v_mul_f32_e32 v14, v14, v98
	v_mul_f32_e32 v15, v15, v99
	v_cvt_pk_bf16_f32 v14, v14, v15
	ds_write_b32 v104, v14 offset:8436
	s_waitcnt lgkmcnt(0)
	s_barrier
; DI int crow(int reg, int h) { return (reg & 3) + 8 * (reg >> 2) + 4 * h; }
; template <int MASK>
; __global__ void __launch_bounds__(256, 2) fwd_megakernel_t(Params p) {
;     ...
;             } else if (n0 < C_DQ) {
;               const int hd = (n0 - C_SBV) >> 7, d = n & 127;
;               u16* dst = sbvT + ((size_t)(b * 4 + hd) * 128 + d) * S_;
; #pragma unroll
;               for (int rg = 0; rg < 4; rg++) {
;                 const int s = (m0 - b * S_) + wm * 64 + i * 32 + 8 * rg + 4 * hh;
;                 uint2 w;
;                 w.x = pack2(acc[i][j][rg * 4 + 0] * rv[rg * 4 + 0], acc[i][j][rg * 4 + 1] * rv[rg * 4 + 1]);
;                 w.y = pack2(acc[i][j][rg * 4 + 2] * rv[rg * 4 + 2], acc[i][j][rg * 4 + 3] * rv[rg * 4 + 3]);
;                 *(uint2*)(dst + s) = w;
;               }
;     ...
;               const int hd = (n0 - C_DV) >> 7, d = n & 127;
;               const int sh = (hd >> 1) * 2;
;               u16* dst = dvT + ((size_t)(b * 6 + hd) * 128 + d) * S_;
; #pragma unroll
;               for (int r = 0; r < 16; r++) {
;                 const int s = (m0 - b * S_) + wm * 64 + i * 32 + crow(r, hh);
;                 const int pos = ((s & ((1 << sh) - 1)) << (13 - sh)) + (s >> sh);
;                 dst[pos] = f2bf(acc[i][j][r] * rv[r]);
;               }
	s_sub_i32 s38, s25, 8
	s_lshr_b32 s39, s38, 1
	s_mov_b32 s39, 0
	s_lshr_b32 s46, s24, 6
	s_mul_i32 s46, s46, 4
	s_add_i32 s46, s46, s38
	s_lshl_b32 s48, s46, 21
	s_lshr_b32 s49, s46, 11
	s_add_u32 s30, s72, s48
	s_addc_u32 s31, s55, s49
	s_and_b32 s48, s24, 63
	s_lshl_b32 s48, s48, 7
	s_lshr_b32 s48, s48, s39
	s_sub_i32 s49, 7, s39
	s_sub_i32 s50, 13, s39
	s_lshr_b32 s46, 0x80, s39
	s_add_i32 s46, s46, -1
	v_and_b32_e32 v100, 63, v152
	v_lshlrev_b32_e32 v100, 1, v100
	v_lshrrev_b32_e32 v101, s49, v100
	v_and_b32_e32 v102, s46, v100
	v_lshlrev_b32_e32 v105, s39, v102
	v_add_u32_e32 v105, v105, v101
	v_lshlrev_b32_e32 v105, 1, v105
	v_lshrrev_b32_e32 v106, 6, v152
	v_mul_u32_u24_e32 v107, 0x2080, v106
	v_add_u32_e32 v105, v105, v107
	s_lshl_b32 s46, 2, s39
	v_add_u32_e32 v108, s46, v105
	v_lshlrev_b32_e32 v109, s50, v101
	v_add3_u32 v109, v109, v102, s48
	v_lshlrev_b32_e32 v109, 1, v109
	s_nop 0
	v_readfirstlane_b32 s46, v106
	s_lshl_b32 s46, s46, 19
	s_add_u32 s30, s30, s46
	s_addc_u32 s31, s31, 0
	ds_read_u16 v110, v105
	ds_read_u16 v118, v108
	ds_read_u16 v111, v105 offset:260
	ds_read_u16 v119, v108 offset:260
	ds_read_u16 v112, v105 offset:520
	ds_read_u16 v120, v108 offset:520
	ds_read_u16 v113, v105 offset:780
	ds_read_u16 v121, v108 offset:780
	ds_read_u16 v114, v105 offset:1040
	ds_read_u16 v122, v108 offset:1040
	ds_read_u16 v115, v105 offset:1300
	ds_read_u16 v123, v108 offset:1300
	ds_read_u16 v116, v105 offset:1560
	ds_read_u16 v124, v108 offset:1560
	ds_read_u16 v117, v105 offset:1820
	ds_read_u16 v125, v108 offset:1820
	s_waitcnt lgkmcnt(0)
	v_lshl_or_b32 v110, v118, 16, v110
	v_lshl_or_b32 v111, v119, 16, v111
	v_lshl_or_b32 v112, v120, 16, v112
	v_lshl_or_b32 v113, v121, 16, v113
	v_lshl_or_b32 v114, v122, 16, v114
	v_lshl_or_b32 v115, v123, 16, v115
	v_lshl_or_b32 v116, v124, 16, v116
	v_lshl_or_b32 v117, v125, 16, v117
	s_add_u32 s34, s30, 0x0
	s_addc_u32 s35, s31, 0
	global_store_dword v109, v110, s[34:35]
	s_add_u32 s34, s30, 0x4000
	s_addc_u32 s35, s31, 0
	global_store_dword v109, v111, s[34:35]
	s_add_u32 s34, s30, 0x8000
	s_addc_u32 s35, s31, 0
	global_store_dword v109, v112, s[34:35]
	s_add_u32 s34, s30, 0xc000
	s_addc_u32 s35, s31, 0
	global_store_dword v109, v113, s[34:35]
	s_add_u32 s34, s30, 0x10000
	s_addc_u32 s35, s31, 0
	global_store_dword v109, v114, s[34:35]
	s_add_u32 s34, s30, 0x14000
	s_addc_u32 s35, s31, 0
	global_store_dword v109, v115, s[34:35]
	s_add_u32 s34, s30, 0x18000
	s_addc_u32 s35, s31, 0
	global_store_dword v109, v116, s[34:35]
	s_add_u32 s34, s30, 0x1c000
	s_addc_u32 s35, s31, 0
	global_store_dword v109, v117, s[34:35]
	ds_read_u16 v110, v105 offset:2080
	ds_read_u16 v118, v108 offset:2080
	ds_read_u16 v111, v105 offset:2340
	ds_read_u16 v119, v108 offset:2340
	ds_read_u16 v112, v105 offset:2600
	ds_read_u16 v120, v108 offset:2600
	ds_read_u16 v113, v105 offset:2860
	ds_read_u16 v121, v108 offset:2860
	ds_read_u16 v114, v105 offset:3120
	ds_read_u16 v122, v108 offset:3120
	ds_read_u16 v115, v105 offset:3380
	ds_read_u16 v123, v108 offset:3380
	ds_read_u16 v116, v105 offset:3640
	ds_read_u16 v124, v108 offset:3640
	ds_read_u16 v117, v105 offset:3900
	ds_read_u16 v125, v108 offset:3900
	s_waitcnt lgkmcnt(0)
; DI int crow(int reg, int h) { return (reg & 3) + 8 * (reg >> 2) + 4 * h; }
; template <int MASK>
; __global__ void __launch_bounds__(256, 2) fwd_megakernel_t(Params p) {
;     ...
;             } else {
;               const int hd = (n0 - C_DV) >> 7, d = n & 127;
;               const int sh = (hd >> 1) * 2;
;               u16* dst = dvT + ((size_t)(b * 6 + hd) * 128 + d) * S_;
; #pragma unroll
;               for (int r = 0; r < 16; r++) {
;                 const int s = (m0 - b * S_) + wm * 64 + i * 32 + crow(r, hh);
;                 const int pos = ((s & ((1 << sh) - 1)) << (13 - sh)) + (s >> sh);
;                 dst[pos] = f2bf(acc[i][j][r] * rv[r]);
;               }
	v_lshl_or_b32 v110, v118, 16, v110
	v_lshl_or_b32 v111, v119, 16, v111
	v_lshl_or_b32 v112, v120, 16, v112
	v_lshl_or_b32 v113, v121, 16, v113
	v_lshl_or_b32 v114, v122, 16, v114
	v_lshl_or_b32 v115, v123, 16, v115
	v_lshl_or_b32 v116, v124, 16, v116
	v_lshl_or_b32 v117, v125, 16, v117
	s_add_u32 s34, s30, 0x20000
	s_addc_u32 s35, s31, 0
	global_store_dword v109, v110, s[34:35]
	s_add_u32 s34, s30, 0x24000
	s_addc_u32 s35, s31, 0
	global_store_dword v109, v111, s[34:35]
	s_add_u32 s34, s30, 0x28000
	s_addc_u32 s35, s31, 0
	global_store_dword v109, v112, s[34:35]
	s_add_u32 s34, s30, 0x2c000
	s_addc_u32 s35, s31, 0
	global_store_dword v109, v113, s[34:35]
	s_add_u32 s34, s30, 0x30000
	s_addc_u32 s35, s31, 0
	global_store_dword v109, v114, s[34:35]
	s_add_u32 s34, s30, 0x34000
	s_addc_u32 s35, s31, 0
	global_store_dword v109, v115, s[34:35]
	s_add_u32 s34, s30, 0x38000
	s_addc_u32 s35, s31, 0
	global_store_dword v109, v116, s[34:35]
	s_add_u32 s34, s30, 0x3c000
	s_addc_u32 s35, s31, 0
	global_store_dword v109, v117, s[34:35]
	ds_read_u16 v110, v105 offset:4160
	ds_read_u16 v118, v108 offset:4160
	ds_read_u16 v111, v105 offset:4420
	ds_read_u16 v119, v108 offset:4420
	ds_read_u16 v112, v105 offset:4680
	ds_read_u16 v120, v108 offset:4680
	ds_read_u16 v113, v105 offset:4940
	ds_read_u16 v121, v108 offset:4940
	ds_read_u16 v114, v105 offset:5200
	ds_read_u16 v122, v108 offset:5200
	ds_read_u16 v115, v105 offset:5460
	ds_read_u16 v123, v108 offset:5460
	ds_read_u16 v116, v105 offset:5720
	ds_read_u16 v124, v108 offset:5720
	ds_read_u16 v117, v105 offset:5980
	ds_read_u16 v125, v108 offset:5980
	s_waitcnt lgkmcnt(0)
	v_lshl_or_b32 v110, v118, 16, v110
	v_lshl_or_b32 v111, v119, 16, v111
	v_lshl_or_b32 v112, v120, 16, v112
	v_lshl_or_b32 v113, v121, 16, v113
	v_lshl_or_b32 v114, v122, 16, v114
	v_lshl_or_b32 v115, v123, 16, v115
	v_lshl_or_b32 v116, v124, 16, v116
	v_lshl_or_b32 v117, v125, 16, v117
	s_add_u32 s34, s30, 0x40000
	s_addc_u32 s35, s31, 0
	global_store_dword v109, v110, s[34:35]
	s_add_u32 s34, s30, 0x44000
	s_addc_u32 s35, s31, 0
	global_store_dword v109, v111, s[34:35]
	s_add_u32 s34, s30, 0x48000
	s_addc_u32 s35, s31, 0
	global_store_dword v109, v112, s[34:35]
	s_add_u32 s34, s30, 0x4c000
	s_addc_u32 s35, s31, 0
	global_store_dword v109, v113, s[34:35]
	s_add_u32 s34, s30, 0x50000
	s_addc_u32 s35, s31, 0
	global_store_dword v109, v114, s[34:35]
	s_add_u32 s34, s30, 0x54000
	s_addc_u32 s35, s31, 0
	global_store_dword v109, v115, s[34:35]
	s_add_u32 s34, s30, 0x58000
	s_addc_u32 s35, s31, 0
	global_store_dword v109, v116, s[34:35]
	s_add_u32 s34, s30, 0x5c000
	s_addc_u32 s35, s31, 0
	global_store_dword v109, v117, s[34:35]
	ds_read_u16 v110, v105 offset:6240
	ds_read_u16 v118, v108 offset:6240
	ds_read_u16 v111, v105 offset:6500
	ds_read_u16 v119, v108 offset:6500
	ds_read_u16 v112, v105 offset:6760
	ds_read_u16 v120, v108 offset:6760
	ds_read_u16 v113, v105 offset:7020
	ds_read_u16 v121, v108 offset:7020
	ds_read_u16 v114, v105 offset:7280
	ds_read_u16 v122, v108 offset:7280
	ds_read_u16 v115, v105 offset:7540
	ds_read_u16 v123, v108 offset:7540
	ds_read_u16 v116, v105 offset:7800
	ds_read_u16 v124, v108 offset:7800
	ds_read_u16 v117, v105 offset:8060
	ds_read_u16 v125, v108 offset:8060
	s_waitcnt lgkmcnt(0)
	v_lshl_or_b32 v110, v118, 16, v110
	v_lshl_or_b32 v111, v119, 16, v111
	v_lshl_or_b32 v112, v120, 16, v112
	v_lshl_or_b32 v113, v121, 16, v113
	v_lshl_or_b32 v114, v122, 16, v114
	v_lshl_or_b32 v115, v123, 16, v115
	v_lshl_or_b32 v116, v124, 16, v116
	v_lshl_or_b32 v117, v125, 16, v117
	s_add_u32 s34, s30, 0x60000
	s_addc_u32 s35, s31, 0
	global_store_dword v109, v110, s[34:35]
	s_add_u32 s34, s30, 0x64000
	s_addc_u32 s35, s31, 0
	global_store_dword v109, v111, s[34:35]
	s_add_u32 s34, s30, 0x68000
	s_addc_u32 s35, s31, 0
	global_store_dword v109, v112, s[34:35]
	s_add_u32 s34, s30, 0x6c000
	s_addc_u32 s35, s31, 0
	global_store_dword v109, v113, s[34:35]
	s_add_u32 s34, s30, 0x70000
	s_addc_u32 s35, s31, 0
	global_store_dword v109, v114, s[34:35]
	s_add_u32 s34, s30, 0x74000
	s_addc_u32 s35, s31, 0
	global_store_dword v109, v115, s[34:35]
	s_add_u32 s34, s30, 0x78000
	s_addc_u32 s35, s31, 0
	global_store_dword v109, v116, s[34:35]
	s_add_u32 s34, s30, 0x7c000
	s_addc_u32 s35, s31, 0
	global_store_dword v109, v117, s[34:35]
	s_branch .LBB0_771

; DI int crow(int reg, int h) { return (reg & 3) + 8 * (reg >> 2) + 4 * h; }
; template <int MASK>
; __global__ void __launch_bounds__(256, 2) fwd_megakernel_t(Params p) {
;     ...
;         const bool isv = (n0 >= C_SBV && n0 < C_DQ) || (n0 >= C_DV && n0 < C_CQ);
;     ...
;             } else if (!isv) {
;               if (n0 == C_KR && n >= C_KR + 64) continue;
; #pragma unroll
;               for (int r = 0; r < 16; r++) {
;                 const int m = m0 + wm * 64 + i * 32 + crow(r, hh);
;                 proj[(size_t)m * NPJ + n] = f2bf(acc[i][j][r] * rv[r]);
;               }
;             } else if (n0 < C_DQ) {
;               const int hd = (n0 - C_SBV) >> 7, d = n & 127;
;               u16* dst = sbvT + ((size_t)(b * 4 + hd) * 128 + d) * S_;
; #pragma unroll
;               for (int rg = 0; rg < 4; rg++) {
;                 const int s = (m0 - b * S_) + wm * 64 + i * 32 + 8 * rg + 4 * hh;
;                 uint2 w;
;                 w.x = pack2(acc[i][j][rg * 4 + 0] * rv[rg * 4 + 0], acc[i][j][rg * 4 + 1] * rv[rg * 4 + 1]);
;                 w.y = pack2(acc[i][j][rg * 4 + 2] * rv[rg * 4 + 2], acc[i][j][rg * 4 + 3] * rv[rg * 4 + 3]);
;                 *(uint2*)(dst + s) = w;
;               }
;             } else {
;               const int hd = (n0 - C_DV) >> 7, d = n & 127;
.Lp1_nodvt:
	s_cmp_lt_i32 s25, 8
	s_cbranch_scc1 .Lp1_nosbv
	s_cmp_lt_i32 s25, 12
	s_cbranch_scc1 .Lp1_sbv
